# stack18 + phase_prep_x back to the plain P layout; the layer-0 QKV GEMM stages A unpermuted and the layer-0 w_o GEMM loads its residual tiles unpermuted (stores stay permuted)
# speedup vs baseline: 1.0062x; 1.0023x over previous
.LBB0_276:
	s_andn2_b64 vcc, exec, s[0:1]
	s_cbranch_vccnz .LBB0_316
	v_and_b32_e32 v236, 15, v2
	v_bfe_u32 v237, v2, 4, 2
	v_lshrrev_b32_e32 v238, 2, v236
	v_lshl_or_b32 v237, v238, 2, v237
	v_and_b32_e32 v236, 3, v236
	v_lshlrev_b32_e32 v236, 3, v236
	v_readlane_b32 s100, v248, 28
	v_and_b32_e32 v240, 63, v2
	v_lshrrev_b32_e32 v241, 4, v240
	v_bfe_u32 v242, v240, 2, 2
	v_sub_u32_e32 v243, 0, v241
	v_and_b32_e32 v243, 3, v243
	v_xor_b32_e32 v242, v242, v243
	v_lshl_or_b32 v241, v241, 2, v242
	v_lshrrev_b32_e32 v243, 7, v2
	v_lshl_or_b32 v241, v243, 4, v241
	v_and_b32_e32 v242, 3, v240
	v_lshlrev_b32_e32 v242, 3, v242
	s_mov_b32 s101, 0x90
	s_lshr_b32 s101, s101, s100
	s_and_b32 s101, s101, 1
	s_cmp_eq_u32 s101, 1
	s_cselect_b64 s[100:101], -1, 0
	v_and_b32_e32 v240, 15, v2
	v_bfe_u32 v243, v2, 4, 2
	v_lshrrev_b32_e32 v244, 2, v240
	v_sub_u32_e32 v245, 0, v244
	v_and_b32_e32 v245, 3, v245
	v_xor_b32_e32 v243, v243, v245
	v_lshlrev_b32_e32 v244, 8, v244
	v_lshl_or_b32 v243, v243, 6, v244
	v_and_b32_e32 v240, 3, v240
	v_lshl_or_b32 v243, v240, 4, v243
	v_bfe_i32 v4, v2, 27, 1
	v_lshlrev_b32_e32 v3, 4, v2
	v_lshrrev_b32_e32 v4, 22, v4
	v_add_u32_e32 v4, v3, v4
	v_and_b32_e32 v4, 0xfffffc00, v4
	v_ashrrev_i32_e32 v0, 31, v2
	v_sub_u32_e32 v4, v3, v4
	v_lshrrev_b32_e32 v0, 26, v0
	v_lshrrev_b32_e32 v5, 4, v4
	v_add_u32_e32 v0, v2, v0
	v_bitop3_b32 v5, v5, v4, 32 bitop3:0x6c
	v_ashrrev_i32_e32 v4, 31, v4
	v_ashrrev_i32_e32 v0, 6, v0
	v_lshrrev_b32_e32 v4, 26, v4
	v_lshlrev_b32_e32 v6, 3, v0
	v_add_u32_e32 v4, v5, v4
	v_and_b32_e32 v6, -16, v6
	v_ashrrev_i32_e32 v4, 6, v4
	v_lshlrev_b32_e32 v0, 5, v0
	v_add_u32_e32 v6, v4, v6
	v_and_b32_e32 v169, 32, v0
	v_mul_i32_i24_e32 v0, 64, v4
	v_sub_u32_e32 v0, v5, v0
	v_lshlrev_b32_e32 v5, 1, v6
	v_lshrrev_b32_e32 v7, 2, v6
	v_and_b32_e32 v4, 3, v4
	s_mov_b32 s5, 0x7fffffe0
	v_ashrrev_i16_sdwa v0, v152, sext(v0) dst_sel:DWORD dst_unused:UNUSED_PAD src0_sel:DWORD src1_sel:BYTE_0
	v_and_b32_e32 v5, 24, v5
	v_and_b32_e32 v7, 4, v7
	v_and_or_b32 v4, v6, s5, v4
	v_bfe_i32 v170, v0, 0, 16
	v_or3_b32 v4, v4, v7, v5
	v_readlane_b32 s18, v248, 43
	v_add_u32_e32 v0, v169, v170
	v_add_u32_e32 v3, 0x2000, v3
	v_mul_lo_u32 v171, v6, s18
	v_mul_lo_u32 v4, v4, s18
	v_add_lshl_u32 v130, v0, v171, 1
	v_mul_lo_u32 v244, v241, s18
	v_add3_u32 v246, v244, v169, v242
	v_lshlrev_b32_e32 v246, 1, v246
	v_lshl_add_u32 v247, s18, 7, v246
	v_cndmask_b32_e64 v130, v130, v246, s[100:101]
	v_add_lshl_u32 v0, v4, v0, 1
	v_ashrrev_i32_e32 v4, 31, v3
	v_lshrrev_b32_e32 v4, 22, v4
	v_add_u32_e32 v4, v3, v4
	v_ashrrev_i32_e32 v4, 10, v4
	v_mul_i32_i24_e32 v5, 0x400, v4
	v_sub_u32_e32 v3, v3, v5
	v_lshrrev_b32_e32 v5, 4, v3
	v_bitop3_b32 v3, v5, v3, 32 bitop3:0x6c
	v_ashrrev_i32_e32 v6, 31, v3
	v_readlane_b32 s0, v248, 39
	v_lshrrev_b32_e32 v6, 26, v6
	v_readlane_b32 s1, v248, 40
	v_lshlrev_b32_e32 v5, 3, v4
	v_add_u32_e32 v6, v3, v6
	s_lshl_b64 s[0:1], s[0:1], 11
	v_readlane_b32 s6, v251, 7
	v_and_b32_e32 v5, -16, v5
	v_ashrrev_i32_e32 v7, 6, v6
	v_readlane_b32 s7, v251, 8
	s_add_u32 s10, s6, s0
	v_add_u32_e32 v5, v7, v5
	v_lshlrev_b32_e32 v4, 5, v4
	v_and_b32_e32 v7, 3, v7
	s_addc_u32 s11, s7, s1
	v_and_b32_e32 v172, 32, v4
	v_and_b32_e32 v4, 0xc0, v6
	v_and_or_b32 v7, v5, s5, v7
	s_ashr_i32 s5, s4, 8
	s_ashr_i32 s1, s4, 6
	v_sub_u32_e32 v3, v3, v4
	v_lshlrev_b32_e32 v4, 1, v5
	v_lshrrev_b32_e32 v6, 2, v5
	s_lshl_b32 s6, s5, 6
	s_lshl_b32 s7, s3, 8
	s_and_b32 s0, s1, 3
	v_ashrrev_i16_sdwa v3, v152, sext(v3) dst_sel:DWORD dst_unused:UNUSED_PAD src0_sel:DWORD src1_sel:BYTE_0
	v_and_b32_e32 v4, 24, v4
	v_and_b32_e32 v6, 4, v6
	v_and_b32_e32 v148, 15, v2
	s_add_i32 s7, s7, s6
	v_bfe_u32 v149, v2, 4, 2
	v_bfe_i32 v173, v3, 0, 16
	v_or3_b32 v4, v7, v6, v4
	s_lshl_b32 s23, s1, 10
	s_lshl_b32 s1, s0, 5
	v_readlane_b32 vcc_lo, v248, 24
	s_nop 0
	s_and_b32 vcc_lo, vcc_lo, 0xffff
	s_cmp_lg_u32 vcc_lo, 4
	s_cselect_b64 vcc, -1, 0
	v_cndmask_b32_e32 v238, v148, v237, vcc
	v_or_b32_e32 v2, s7, v238
	s_lshl_b32 s7, s2, 8
	v_add_u32_e32 v3, v172, v173
	v_mul_lo_u32 v174, v5, s18
	v_mul_lo_u32 v4, v4, s18
	v_lshlrev_b32_e32 v168, 3, v149
	s_or_b32 s7, s7, s1
	v_or_b32_e32 v8, 16, v2
	v_add_lshl_u32 v132, v3, v174, 1
	v_cndmask_b32_e64 v132, v132, v247, s[100:101]
	v_add_lshl_u32 v134, v4, v3, 1
	v_cndmask_b32_e32 v239, v168, v236, vcc
	v_or_b32_e32 v4, s7, v239
	v_ashrrev_i32_e32 v3, 31, v2
	v_ashrrev_i32_e32 v9, 31, v8
	v_ashrrev_i32_e32 v5, 31, v4
	v_lshlrev_b64 v[6:7], 11, v[2:3]
	v_lshlrev_b64 v[8:9], 11, v[8:9]
	v_lshl_add_u64 v[6:7], s[10:11], 0, v[6:7]
	v_lshlrev_b64 v[4:5], 1, v[4:5]
	v_lshl_add_u64 v[8:9], s[10:11], 0, v[8:9]
	v_lshl_add_u64 v[6:7], v[6:7], 0, v[4:5]
	v_lshl_add_u64 v[8:9], v[8:9], 0, v[4:5]
	global_load_dwordx4 v[62:65], v[6:7], off
	global_load_dwordx4 v[54:57], v[6:7], off offset:256
	global_load_dwordx4 v[58:61], v[8:9], off
	global_load_dwordx4 v[46:49], v[8:9], off offset:256
	v_or_b32_e32 v8, 32, v2
	v_or_b32_e32 v2, 48, v2
	v_ashrrev_i32_e32 v9, 31, v8
	v_ashrrev_i32_e32 v3, 31, v2
	v_lshlrev_b64 v[8:9], 11, v[8:9]
	v_lshlrev_b64 v[2:3], 11, v[2:3]
	v_lshl_add_u64 v[8:9], s[10:11], 0, v[8:9]
	v_lshl_add_u64 v[2:3], s[10:11], 0, v[2:3]
	s_mov_b32 s7, 0x40000
	v_lshl_add_u64 v[8:9], v[8:9], 0, v[4:5]
	v_lshl_add_u64 v[2:3], v[2:3], 0, v[4:5]
	v_add_co_u32_e32 v4, vcc, s7, v6
	s_mov_b64 s[90:91], 0x40000
	s_nop 0
	v_addc_co_u32_e32 v5, vcc, 0, v7, vcc
	s_mov_b32 s7, 0x48000
	global_load_dwordx4 v[50:53], v[8:9], off
	global_load_dwordx4 v[38:41], v[8:9], off offset:256
	global_load_dwordx4 v[42:45], v[2:3], off
	global_load_dwordx4 v[30:33], v[2:3], off offset:256
	v_lshl_add_u64 v[2:3], v[6:7], 0, s[90:91]
	global_load_dwordx4 v[34:37], v[4:5], off
	global_load_dwordx4 v[18:21], v[2:3], off offset:256
	v_add_co_u32_e32 v4, vcc, s7, v6
	s_mov_b64 s[92:93], 0x48000
	s_nop 0
	v_addc_co_u32_e32 v5, vcc, 0, v7, vcc
	s_mov_b32 s7, 0x50000
	v_lshl_add_u64 v[2:3], v[6:7], 0, s[92:93]
	global_load_dwordx4 v[26:29], v[4:5], off
	global_load_dwordx4 v[10:13], v[2:3], off offset:256
	v_add_co_u32_e32 v4, vcc, s7, v6
	s_lshl_b32 s80, s18, 8
	s_mov_b64 s[98:99], 0x50000
	v_addc_co_u32_e32 v5, vcc, 0, v7, vcc
	s_mov_b64 s[8:9], 0x58000
	s_mov_b32 s7, 0x58000
	s_lshl_b64 s[14:15], s[80:81], 1
	v_lshl_add_u64 v[2:3], v[6:7], 0, s[98:99]
	v_lshl_add_u64 v[22:23], v[6:7], 0, s[8:9]
	v_add_co_u32_e32 v6, vcc, s7, v6
	s_ashr_i32 s7, s3, 31
	s_mul_i32 s7, s14, s7
	s_mul_hi_u32 s8, s14, s3
	s_add_i32 s7, s8, s7
	s_bfe_u32 s8, s18, 0x10017
	s_mul_i32 s9, s8, s3
	s_add_i32 s7, s7, s9
	s_ashr_i32 s9, s2, 31
	s_mul_i32 s9, s14, s9
	s_mul_hi_u32 s16, s14, s2
	s_add_i32 s9, s16, s9
	s_mul_i32 s8, s8, s2
	s_add_i32 s9, s9, s8
	s_mul_i32 s8, s14, s2
	v_readlane_b32 s16, v248, 46
	v_readlane_b32 s17, v248, 47
	s_add_u32 s54, s16, s8
	s_addc_u32 s55, s17, s9
	s_add_i32 s58, s23, 0
	v_addc_co_u32_e32 v7, vcc, 0, v7, vcc
	s_add_i32 m0, s58, 0x10000
	s_waitcnt lgkmcnt(0)
	global_load_dwordx4 v[14:17], v[4:5], off
	s_nop 0
	global_load_dwordx4 v[2:5], v[2:3], off offset:256
	s_nop 0
	global_load_dwordx4 v[6:9], v[6:7], off
	s_nop 0
	global_load_dwordx4 v[22:25], v[22:23], off offset:256
	v_mov_b32_e32 v135, v1
	global_load_lds_dwordx4 v0, s[54:55]
	s_add_i32 m0, s58, 0x12000
	s_add_u32 s8, s54, s80
	global_load_lds_dwordx4 v134, s[54:55]
	s_addc_u32 s9, s55, 0
	s_add_i32 m0, s58, 0x14000
	s_mul_i32 s13, s14, s3
	global_load_lds_dwordx4 v0, s[8:9]
	s_add_i32 m0, s58, 0x16000
	v_lshl_add_u64 v[140:141], s[8:9], 0, v[0:1]
	v_lshl_add_u64 v[142:143], s[8:9], 0, v[134:135]
	global_load_lds_dwordx4 v134, s[8:9]
	v_readlane_b32 s8, v248, 48
	v_readlane_b32 s9, v248, 49
	s_add_u32 s56, s8, s13
	s_addc_u32 s57, s9, s7
	s_add_i32 s59, s58, 0x2000
	s_mov_b32 m0, s58
	s_add_u32 s8, s56, s80
	global_load_lds_dwordx4 v130, s[56:57]
	s_mov_b32 m0, s59
	s_addc_u32 s9, s57, 0
	s_add_i32 s60, s58, 0x4000
	global_load_lds_dwordx4 v132, s[56:57]
	s_mov_b32 m0, s60
	s_add_i32 s61, s58, 0x6000
	global_load_lds_dwordx4 v130, s[8:9]
	s_mov_b32 m0, s61
	s_cmp_eq_u32 s5, 1
	global_load_lds_dwordx4 v132, s[8:9]
	v_mov_b32_e32 v131, v1
	v_mov_b32_e32 v133, v1
	s_cselect_b64 s[8:9], -1, 0
	v_lshl_add_u64 v[136:137], s[54:55], 0, v[0:1]
	v_lshl_add_u64 v[138:139], s[54:55], 0, v[134:135]
	v_lshl_add_u64 v[144:145], s[56:57], 0, v[130:131]
	v_lshl_add_u64 v[146:147], s[56:57], 0, v[132:133]
	v_writelane_b32 v248, s8, 29
	s_cmp_lg_u32 s5, 1
	s_nop 0
	v_writelane_b32 v248, s9, 30
	s_cbranch_scc1 .LBB0_279
	s_barrier

.LBB0_311:
	s_or_b64 exec, exec, s[54:55]
	s_and_b64 vcc, exec, s[8:9]
	s_mov_b64 s[2:3], -1
	s_cbranch_vccnz .LBB0_281
	v_and_b32_e32 v236, 15, v150
	v_bfe_u32 v237, v150, 4, 2
	v_lshrrev_b32_e32 v238, 2, v236
	v_lshl_or_b32 v237, v238, 2, v237
	v_and_b32_e32 v236, 3, v236
	v_lshlrev_b32_e32 v236, 3, v236
	v_and_or_b32 v238, v146, -16, v237
	v_lshrrev_b32_e32 v239, 5, v168
	v_lshl_or_b32 v239, v239, 5, v236
	v_readlane_b32 s2, v248, 24
	s_nop 0
	s_and_b32 s2, s2, 0xffff
	s_cmp_lg_u32 s2, 4
	s_cselect_b64 vcc, -1, 0
	v_cndmask_b32_e32 v238, v146, v238, vcc
	v_cndmask_b32_e32 v239, v168, v239, vcc
	v_lshl_add_u32 v2, s17, 8, v238
	v_or_b32_e32 v8, 16, v2
	v_lshl_or_b32 v4, s16, 8, v239
	s_waitcnt lgkmcnt(0)
	v_ashrrev_i32_e32 v3, 31, v2
	v_ashrrev_i32_e32 v9, 31, v8
	v_ashrrev_i32_e32 v5, 31, v4
	v_lshlrev_b64 v[6:7], 11, v[2:3]
	v_lshlrev_b64 v[8:9], 11, v[8:9]
	v_lshl_add_u64 v[6:7], s[10:11], 0, v[6:7]
	v_lshlrev_b64 v[4:5], 1, v[4:5]
	v_lshl_add_u64 v[8:9], s[10:11], 0, v[8:9]
	v_lshl_add_u64 v[6:7], v[6:7], 0, v[4:5]
	v_lshl_add_u64 v[8:9], v[8:9], 0, v[4:5]
	global_load_dwordx4 v[62:65], v[6:7], off
	global_load_dwordx4 v[54:57], v[6:7], off offset:256
	global_load_dwordx4 v[58:61], v[8:9], off
	global_load_dwordx4 v[46:49], v[8:9], off offset:256
	v_or_b32_e32 v8, 32, v2
	v_or_b32_e32 v2, 48, v2
	v_ashrrev_i32_e32 v9, 31, v8
	v_ashrrev_i32_e32 v3, 31, v2
	v_lshlrev_b64 v[8:9], 11, v[8:9]
	v_lshlrev_b64 v[2:3], 11, v[2:3]
	v_lshl_add_u64 v[8:9], s[10:11], 0, v[8:9]
	v_lshl_add_u64 v[2:3], s[10:11], 0, v[2:3]
	s_mov_b32 s2, 0x40000
	v_lshl_add_u64 v[8:9], v[8:9], 0, v[4:5]
	v_lshl_add_u64 v[2:3], v[2:3], 0, v[4:5]
	v_add_co_u32_e32 v4, vcc, s2, v6
	s_mov_b32 s2, 0x48000
	s_nop 0
	v_addc_co_u32_e32 v5, vcc, 0, v7, vcc
	global_load_dwordx4 v[50:53], v[8:9], off
	global_load_dwordx4 v[38:41], v[8:9], off offset:256
	global_load_dwordx4 v[42:45], v[2:3], off
	global_load_dwordx4 v[30:33], v[2:3], off offset:256
	v_lshl_add_u64 v[2:3], v[6:7], 0, s[90:91]
	global_load_dwordx4 v[34:37], v[4:5], off
	global_load_dwordx4 v[18:21], v[2:3], off offset:256
	v_add_co_u32_e32 v4, vcc, s2, v6
	v_lshl_add_u64 v[2:3], v[6:7], 0, s[92:93]
	s_nop 0
	v_addc_co_u32_e32 v5, vcc, 0, v7, vcc
	global_load_dwordx4 v[26:29], v[4:5], off
	global_load_dwordx4 v[10:13], v[2:3], off offset:256
	v_add_co_u32_e32 v4, vcc, 0x50000, v6
	s_mov_b64 s[2:3], 0x58000
	s_nop 0
	v_addc_co_u32_e32 v5, vcc, 0, v7, vcc
	v_lshl_add_u64 v[2:3], v[6:7], 0, s[98:99]
	v_lshl_add_u64 v[22:23], v[6:7], 0, s[2:3]
	v_add_co_u32_e32 v6, vcc, 0x58000, v6
	global_load_dwordx4 v[14:17], v[4:5], off
	s_nop 0
	global_load_dwordx4 v[2:5], v[2:3], off offset:256
	v_addc_co_u32_e32 v7, vcc, 0, v7, vcc
	global_load_dwordx4 v[6:9], v[6:7], off
	s_nop 0
	global_load_dwordx4 v[22:25], v[22:23], off offset:256
	v_readlane_b32 s2, v248, 29
	v_readlane_b32 s3, v248, 30
	s_andn2_b64 vcc, exec, s[2:3]
	s_cbranch_vccnz .LBB0_280
	s_barrier
	s_branch .LBB0_280

.LBB0_406:
	v_bfe_i32 v4, v2, 27, 1
	v_lshlrev_b32_e32 v3, 4, v2
	v_lshrrev_b32_e32 v4, 22, v4
	v_add_u32_e32 v4, v3, v4
	v_and_b32_e32 v4, 0xfffffc00, v4
	v_ashrrev_i32_e32 v0, 31, v2
	v_sub_u32_e32 v4, v3, v4
	v_lshrrev_b32_e32 v0, 26, v0
	v_lshrrev_b32_e32 v5, 4, v4
	v_add_u32_e32 v0, v2, v0
	v_bitop3_b32 v5, v5, v4, 32 bitop3:0x6c
	v_ashrrev_i32_e32 v4, 31, v4
	v_ashrrev_i32_e32 v0, 6, v0
	v_lshrrev_b32_e32 v4, 26, v4
	v_lshlrev_b32_e32 v6, 3, v0
	v_add_u32_e32 v4, v5, v4
	v_and_b32_e32 v6, -16, v6
	v_ashrrev_i32_e32 v4, 6, v4
	v_lshlrev_b32_e32 v0, 5, v0
	v_add_u32_e32 v6, v4, v6
	v_and_b32_e32 v14, 32, v0
	v_mul_i32_i24_e32 v0, 64, v4
	v_sub_u32_e32 v0, v5, v0
	v_lshlrev_b32_e32 v5, 1, v6
	v_lshrrev_b32_e32 v7, 2, v6
	v_and_b32_e32 v4, 3, v4
	s_mov_b32 s2, 0x7fffffe0
	v_ashrrev_i16_sdwa v0, v152, sext(v0) dst_sel:DWORD dst_unused:UNUSED_PAD src0_sel:DWORD src1_sel:BYTE_0
	v_and_b32_e32 v5, 24, v5
	v_and_b32_e32 v7, 4, v7
	v_and_or_b32 v4, v6, s2, v4
	v_bfe_i32 v16, v0, 0, 16
	v_or3_b32 v4, v4, v7, v5
	v_readlane_b32 s15, v248, 43
	v_add_u32_e32 v0, v14, v16
	v_add_u32_e32 v3, 0x2000, v3
	v_mul_lo_u32 v17, v6, s15
	v_mul_lo_u32 v4, v4, s15
	v_add_lshl_u32 v130, v0, v17, 1
	v_readlane_b32 s100, v248, 24
	s_nop 0
	s_bfe_u32 s100, s100, 0x80008
	s_cmp_lg_u32 s100, 0
	s_cselect_b64 s[100:101], -1, 0
	v_and_b32_e32 v240, 63, v150
	v_lshrrev_b32_e32 v241, 4, v240
	v_bfe_u32 v242, v240, 2, 2
	v_sub_u32_e32 v243, 0, v241
	v_and_b32_e32 v243, 3, v243
	v_xor_b32_e32 v242, v242, v243
	v_lshl_or_b32 v241, v241, 2, v242
	v_lshrrev_b32_e32 v243, 7, v150
	v_lshl_or_b32 v241, v243, 4, v241
	v_and_b32_e32 v242, 3, v240
	v_lshlrev_b32_e32 v242, 3, v242
	v_mul_lo_u32 v244, v241, s15
	v_add3_u32 v246, v244, v14, v242
	v_lshlrev_b32_e32 v246, 1, v246
	v_lshl_add_u32 v247, s15, 7, v246
	v_cndmask_b32_e64 v130, v130, v246, s[100:101]
	v_and_b32_e32 v240, 15, v150
	v_bfe_u32 v243, v150, 4, 2
	v_lshrrev_b32_e32 v244, 2, v240
	v_sub_u32_e32 v245, 0, v244
	v_and_b32_e32 v245, 3, v245
	v_xor_b32_e32 v243, v243, v245
	v_lshlrev_b32_e32 v244, 8, v244
	v_lshl_or_b32 v243, v243, 6, v244
	v_and_b32_e32 v240, 3, v240
	v_lshl_or_b32 v243, v240, 4, v243
	v_add_lshl_u32 v0, v4, v0, 1
	v_ashrrev_i32_e32 v4, 31, v3
	v_lshrrev_b32_e32 v4, 22, v4
	v_add_u32_e32 v4, v3, v4
	v_ashrrev_i32_e32 v4, 10, v4
	v_mul_i32_i24_e32 v5, 0x400, v4
	v_sub_u32_e32 v3, v3, v5
	v_lshrrev_b32_e32 v5, 4, v3
	v_bitop3_b32 v3, v5, v3, 32 bitop3:0x6c
	v_ashrrev_i32_e32 v6, 31, v3
	v_lshrrev_b32_e32 v6, 26, v6
	v_lshlrev_b32_e32 v5, 3, v4
	v_add_u32_e32 v6, v3, v6
	v_and_b32_e32 v5, -16, v5
	v_ashrrev_i32_e32 v7, 6, v6
	v_lshlrev_b32_e32 v4, 5, v4
	v_add_u32_e32 v5, v7, v5
	v_and_b32_e32 v18, 32, v4
	v_and_b32_e32 v4, 0xc0, v6
	s_ashr_i32 s13, s0, 8
	s_ashr_i32 s6, s0, 6
	v_bfe_u32 v15, v2, 4, 2
	v_sub_u32_e32 v3, v3, v4
	v_lshlrev_b32_e32 v4, 1, v5
	v_lshrrev_b32_e32 v6, 2, v5
	v_and_b32_e32 v7, 3, v7
	s_lshl_b32 s7, s13, 6
	s_lshl_b32 s8, s62, 8
	s_sext_i32_i16 s63, s1
	s_and_b32 s1, s6, 3
	v_ashrrev_i16_sdwa v3, v152, sext(v3) dst_sel:DWORD dst_unused:UNUSED_PAD src0_sel:DWORD src1_sel:BYTE_0
	v_and_b32_e32 v4, 24, v4
	v_and_b32_e32 v6, 4, v6
	v_and_or_b32 v7, v5, s2, v7
	v_and_b32_e32 v21, 15, v2
	s_lshl_b32 s30, s6, 10
	v_lshlrev_b32_e32 v22, 4, v15
	s_lshl_b32 s6, s13, 13
	s_add_i32 s8, s8, s7
	v_bfe_i32 v19, v3, 0, 16
	v_or3_b32 v4, v7, v6, v4
	v_or3_b32 v2, s8, v22, v21
	s_lshl_b32 s8, s1, 11
	s_add_i32 s9, s6, 0
	v_readlane_b32 s96, v248, 52
	v_add_u32_e32 v3, v18, v19
	v_mul_lo_u32 v20, v5, s15
	v_mul_lo_u32 v4, v4, s15
	s_add_i32 s8, s9, s8
	v_readlane_b32 s97, v248, 53
	v_add_lshl_u32 v132, v3, v20, 1
	v_cndmask_b32_e64 v132, v132, v247, s[100:101]
	v_add_lshl_u32 v134, v4, v3, 1
	v_ashrrev_i32_e32 v3, 31, v2
	s_add_i32 s31, s8, 0x21010
	s_lshl_b32 s80, s15, 8
	v_lshl_add_u64 v[2:3], v[2:3], 4, s[96:97]
	s_mov_b32 m0, s31
	s_lshl_b64 s[2:3], s[80:81], 1
	global_load_lds_dwordx4 v[2:3], off
	s_add_i32 m0, s8, 0x21410
	s_ashr_i32 s8, s62, 31
	s_mul_i32 s8, s2, s8
	s_mul_hi_u32 s9, s2, s62
	s_add_i32 s8, s9, s8
	s_bfe_u32 s9, s15, 0x10017
	s_mul_i32 s10, s9, s62
	s_add_i32 s10, s8, s10
	s_ashr_i32 s8, s63, 31
	s_mul_i32 s8, s2, s8
	s_mul_hi_u32 s14, s2, s63
	s_add_i32 s8, s14, s8
	s_mul_i32 s9, s9, s63
	v_readlane_b32 s90, v248, 46
	s_add_i32 s8, s8, s9
	s_mul_i32 s9, s2, s63
	v_readlane_b32 s91, v248, 47
	s_add_u32 s20, s90, s9
	v_lshl_add_u64 v[2:3], v[2:3], 0, s[82:83]
	s_addc_u32 s21, s91, s8
	s_add_i32 s35, s30, 0
	global_load_lds_dwordx4 v[2:3], off
	s_add_i32 m0, s35, 0x10000
	v_readlane_b32 s92, v248, 48
	global_load_lds_dwordx4 v0, s[20:21]
	s_add_i32 m0, s35, 0x12000
	s_add_u32 s8, s20, s80
	global_load_lds_dwordx4 v134, s[20:21]
	s_addc_u32 s9, s21, 0
	s_add_i32 m0, s35, 0x14000
	s_mul_i32 s11, s2, s62
	global_load_lds_dwordx4 v0, s[8:9]
	s_add_i32 m0, s35, 0x16000
	v_readlane_b32 s93, v248, 49
	s_add_u32 s16, s92, s11
	s_addc_u32 s17, s93, s10
	s_add_i32 s52, s35, 0x2000
	global_load_lds_dwordx4 v134, s[8:9]
	s_mov_b32 m0, s35
	s_add_u32 s10, s16, s80
	global_load_lds_dwordx4 v130, s[16:17]
	s_mov_b32 m0, s52
	s_addc_u32 s11, s17, 0
	s_add_i32 s53, s35, 0x4000
	global_load_lds_dwordx4 v132, s[16:17]
	s_mov_b32 m0, s53
	s_add_i32 s54, s35, 0x6000
	global_load_lds_dwordx4 v130, s[10:11]
	s_mov_b32 m0, s54
	v_mov_b32_e32 v135, v1
	global_load_lds_dwordx4 v132, s[10:11]
	v_mov_b32_e32 v131, v1
	v_mov_b32_e32 v133, v1
	s_cmp_eq_u32 s13, 1
	v_lshl_add_u64 v[10:11], s[20:21], 0, v[0:1]
	v_lshl_add_u64 v[6:7], s[20:21], 0, v[134:135]
	v_lshl_add_u64 v[4:5], s[8:9], 0, v[0:1]
	v_lshl_add_u64 v[2:3], s[8:9], 0, v[134:135]
	v_lshl_add_u64 v[8:9], s[16:17], 0, v[130:131]
	s_cselect_b64 s[8:9], -1, 0
	s_cmp_lg_u32 s13, 1
	v_lshl_add_u64 v[12:13], s[16:17], 0, v[132:133]
	v_readlane_b32 s73, v250, 31
	s_cbranch_scc1 .LBB0_408
	s_barrier
.LBB0_408:
	s_add_i32 m0, s35, 0x18000
	v_lshl_add_u64 v[10:11], v[10:11], 0, s[94:95]
	s_waitcnt vmcnt(2)
	s_barrier
	global_load_lds_dwordx4 v[10:11], off
	v_lshl_add_u64 v[6:7], v[6:7], 0, s[94:95]
	s_add_i32 m0, s35, 0x1a000
	s_add_i32 s55, s35, 0x8000
	global_load_lds_dwordx4 v[6:7], off
	v_lshl_add_u64 v[6:7], v[8:9], 0, s[94:95]
	s_mov_b32 m0, s55
	s_add_i32 s56, s35, 0xa000
	global_load_lds_dwordx4 v[6:7], off
	v_lshl_add_u64 v[6:7], v[12:13], 0, s[94:95]
	s_mov_b32 m0, s56
	v_lshl_add_u64 v[4:5], v[4:5], 0, s[94:95]
	global_load_lds_dwordx4 v[6:7], off
	s_add_i32 m0, s35, 0x1c000
	v_lshl_add_u64 v[2:3], v[2:3], 0, s[94:95]
	global_load_lds_dwordx4 v[4:5], off
	s_add_i32 m0, s35, 0x1e000
	v_or_b32_e32 v142, s7, v21
	global_load_lds_dwordx4 v[2:3], off
	v_lshlrev_b32_e32 v3, 6, v142
	s_movk_i32 s7, 0x3c0
	v_lshlrev_b32_e32 v4, 2, v142
	v_lshlrev_b32_e32 v2, 3, v15
	v_and_or_b32 v3, v3, s7, v22
	v_and_b32_e32 v4, 32, v4
	v_lshlrev_b32_e32 v5, 2, v21
	v_bitop3_b32 v4, v3, s6, v4 bitop3:0xde
	v_lshl_or_b32 v3, v21, 6, v22
	s_lshl_b32 s6, s1, 12
	v_and_b32_e32 v5, 32, v5
	v_lshl_or_b32 v144, s1, 5, v2
	v_add_u32_e32 v2, v17, v14
	s_lshr_b32 s57, s15, 6
	v_bitop3_b32 v143, v3, s6, v5 bitop3:0xde
	v_add_lshl_u32 v2, v2, v16, 1
	v_cndmask_b32_e64 v2, v2, v246, s[100:101]
	v_mov_b32_e32 v3, v1
	s_waitcnt vmcnt(6)
	s_add_i32 s58, s57, -2
	v_lshl_add_u64 v[136:137], s[80:81], 0, v[2:3]
	v_add_u32_e32 v2, v20, v18
	s_cmpk_lt_u32 s0, 0x100
	v_lshlrev_b32_e32 v5, 4, v21
	v_add_lshl_u32 v2, v2, v19, 1
	v_cndmask_b32_e64 v2, v2, v247, s[100:101]
	v_or_b32_e32 v145, v142, v22
	s_cselect_b64 s[10:11], -1, 0
	s_mov_b32 s13, s81
	v_lshl_add_u64 v[138:139], s[80:81], 0, v[2:3]
	s_mov_b32 s59, 0
	v_add_u32_e32 v146, 0, v4
	v_lshrrev_b32_e32 v245, 10, v146
	v_lshl_or_b32 v245, v245, 10, v243
	v_cndmask_b32_e64 v146, v146, v245, s[100:101]
	v_add_u32_e32 v147, s31, v5
	s_barrier
	s_branch .LBB0_411
